# v24 + FFN-in fast path: lane-to-(row,channel) mapping chosen so every ds_read_b128 hardware lane group hits 64 distinct banks (strategy 6: LDS bank conflicts)
# speedup vs baseline: 1.0072x; 1.0072x over previous
; DI void stf8(float* p, const F8& f) { *(float4*)p = make_float4(f.v[0], f.v[1], f.v[2], f.v[3]); *(float4*)(p + 4) = make_float4(f.v[4], f.v[5], f.v[6], f.v[7]); }
; DI void stb8(bf16_t* p, const F8& f) { *(uint4*)p = pack8(f); }
; DI float siluf(float x) { return x / (1.f + __expf(-x)); }
; template <int MODE>
; DI void gemm_epilogue(const float* Cs, int m0, int n0, const Epi& ep) {
;     ...
;         const int mt = m0 >> 7, ch0 = (n0 >> 7) * 64, c8 = (tid & 7) * 8, ch = ch0 + c8;
;         const float* cw = ep.c0;
;         const F8 w0 = ldf8(cw + ch), w1 = ldf8(cw + 2816 + ch), w2 = ldf8(cw + 2 * 2816 + ch);
;         const bool defer01 = (m0 < MP) && ((m0 & 8191) != 0);
; #pragma unroll
;         for (int it = 0; it < 2; ++it) {
;             const int i = (tid >> 3) + 64 * it, r = m0 + i;
;             int sq, pos, len; rowinfo(r, sq, pos, len);
;             const F8 g0 = ldf8(Cs + i * LDC + c8), up = ldf8(Cs + i * LDC + 64 + c8);
;             if (i >= 126) stf8(ep.f0 + ((size_t)mt * 2 + (i - 126)) * 2816 + ch, g0);
;             if (i < 2) { stf8(ep.f1 + ((size_t)mt * 2 + i) * 2816 + ch, g0); stf8(ep.f2 + ((size_t)mt * 2 + i) * 2816 + ch, up); }
;             if (pos >= len - 2) {
;                 float* so = sq < 4 ? ep.out + O_PFF + (((size_t)ep.layer * 4 + sq) * 2 + (pos - (len - 2))) * 2816
;                                    : ep.out + O_SFF + (((size_t)ep.layer * 8 + (sq - 4)) * 2 + (pos - (len - 2))) * 2816;
;                 stf8(so + ch, g0);
;             }
;             if (i < 2 && defer01) continue;
;             F8 g1, g2;
;             const float* hist = sq >= 4 ? ep.c1 + ((size_t)ep.layer * 8 + (sq - 4)) * 2 * 2816 + ch : nullptr;
;             if (pos >= 1) g1 = ldf8(Cs + (i - 1) * LDC + c8);
;             else if (hist) g1 = ldf8(hist + 2816);
;             else { for (int e = 0; e < 8; ++e) g1.v[e] = 0.f; }
;             if (pos >= 2) g2 = ldf8(Cs + (i - 2) * LDC + c8);
;             else if (hist) g2 = ldf8(hist + (size_t)pos * 2816);
;             else { for (int e = 0; e < 8; ++e) g2.v[e] = 0.f; }
;             F8 o;
; #pragma unroll
;             for (int e = 0; e < 8; ++e) o.v[e] = siluf(w0.v[e] * g2.v[e] + w1.v[e] * g1.v[e] + w2.v[e] * g0.v[e]) * up.v[e];
;             stb8(ep.b0 + (size_t)r * 2816 + ch, o);
.Lffn_fast:
	s_lshl_b32 s54, s27, 8
	s_lshl_b32 s30, s26, 7
	s_lshl_b32 s31, s27, 2
	v_bfe_u32 v64, v250, 2, 3
	v_mov_b32_e32 v65, 0x31130220
	v_lshlrev_b32_e32 v64, 2, v64
	v_bfe_u32 v66, v250, 5, 1
	v_lshrrev_b32_e32 v195, 6, v250
	v_lshrrev_b32_e32 v65, v64, v65
	v_lshlrev_b32_e32 v195, 3, v195
	v_and_b32_e32 v65, 3, v65
	v_lshl_add_u32 v195, v66, 2, v195
	v_bfe_u32 v212, v250, 3, 1
	v_add_u32_e32 v195, v195, v65
	v_and_b32_e32 v67, 3, v250
	v_lshlrev_b32_e32 v212, 5, v212
	v_lshl_or_b32 v212, v67, 3, v212
	v_add_u32_e32 v64, s30, v212
	v_add_u32_e32 v65, s54, v195
	s_movk_i32 s0, 0x1600
	v_add_u32_e32 v66, s31, v195
	v_mul_lo_u32 v65, v65, s0
	v_mul_lo_u32 v66, v66, s3
	v_mul_u32_u24_e32 v197, 0x210, v195
	v_lshl_add_u32 v65, v64, 1, v65
	v_lshlrev_b32_e32 v64, 2, v64
	v_lshl_add_u32 v67, v212, 2, 16
	v_add_u32_e32 v66, v66, v64
	v_add_u32_e32 v197, v197, v67
	v_cmp_lt_u32_e64 s[40:41], 1, v195
	v_cmp_gt_u32_e64 s[42:43], 2, v195
	v_cmp_lt_u32_e64 s[44:45], 61, v195
	v_add_u32_e32 v196, 0xfffffbe0, v197
	v_max_i32_e32 v196, v196, v67
	s_mov_b32 s30, 0xbfb8aa3b
	s_mov_b32 s31, 0xbfb8aa3b
	global_load_dwordx4 v[128:131], v64, s[6:7] offset:0
	global_load_dwordx4 v[132:135], v64, s[6:7] offset:16
	global_load_dwordx4 v[136:139], v64, s[14:15] offset:0
	global_load_dwordx4 v[140:143], v64, s[14:15] offset:16
	global_load_dwordx4 v[144:147], v64, s[18:19] offset:0
	global_load_dwordx4 v[148:151], v64, s[18:19] offset:16
	ds_write_b128 v194, v[96:99]
	ds_write_b128 v194, v[100:103] offset:64
	ds_write_b128 v194, v[104:107] offset:8448
	ds_write_b128 v194, v[108:111] offset:8512
	ds_write_b128 v194, v[112:115] offset:16896
	ds_write_b128 v194, v[116:119] offset:16960
	ds_write_b128 v194, v[120:123] offset:25344
	ds_write_b128 v194, v[124:127] offset:25408
	s_waitcnt lgkmcnt(0)
	s_barrier
	ds_read_b128 v[96:99], v197
	ds_read_b128 v[100:103], v197 offset:16
	ds_read_b128 v[104:107], v197 offset:256
	ds_read_b128 v[108:111], v197 offset:272
	ds_read_b128 v[112:115], v196 offset:528
	ds_read_b128 v[116:119], v196 offset:544
	ds_read_b128 v[120:123], v196
	ds_read_b128 v[124:127], v196 offset:16
	s_waitcnt vmcnt(0)
	s_mov_b64 exec, s[42:43]
	s_cbranch_execz .Lffn_f1
	s_waitcnt lgkmcnt(4)
	global_store_dwordx4 v66, v[96:99], s[80:81] offset:0
	global_store_dwordx4 v66, v[100:103], s[80:81] offset:16
	global_store_dwordx4 v66, v[104:107], s[82:83] offset:0
	global_store_dwordx4 v66, v[108:111], s[82:83] offset:16
